# GEMM K-loops: load-segment scalar address/counter arithmetic hoisted into the preceding compute segment's MFMA shadow (9-13 SALU per iteration)
# baseline (speedup 1.0000x reference)
.LBB0_120:
	ds_read_b128 v[130:133], v245
	ds_read_b128 v[134:137], v245 offset:1024
	ds_read_b128 v[138:141], v245 offset:2048
	ds_read_b128 v[142:145], v245 offset:3072
	s_waitcnt vmcnt(0)
	ds_read_b128 v[146:149], v246
	ds_read_b128 v[150:153], v246 offset:1024
	ds_read_b128 v[154:157], v246 offset:2048
	ds_read_b128 v[158:161], v246 offset:3072
	s_add_u32 s16, s6, 0xfffc0080
	s_addc_u32 s17, s7, -1
	s_cmp_eq_u32 s40, 12
	s_cselect_b32 s79, s1, s17
	s_cselect_b32 s78, s2, s16
	s_cselect_b32 s17, s3, s37
	s_cselect_b32 s16, s9, s35
	s_add_i32 m0, s71, 0xc000
	ds_read_b128 v[162:165], v247
	ds_read_b128 v[166:169], v247 offset:1024
	ds_read_b128 v[170:173], v247 offset:2048
	ds_read_b128 v[174:177], v247 offset:3072
	ds_read_b128 v[178:181], v247 offset:4096
	ds_read_b128 v[182:185], v247 offset:5120
	ds_read_b128 v[186:189], v247 offset:6144
	ds_read_b128 v[190:193], v247 offset:7168
	global_load_lds_dwordx4 v226, s[6:7]
	s_add_i32 m0, s71, 0xe000
	s_nop 0
	global_load_lds_dwordx4 v228, s[6:7]
	s_waitcnt vmcnt(8)
	s_waitcnt lgkmcnt(0)
	s_barrier
	s_setprio 1
	s_waitcnt lgkmcnt(0)
	v_mfma_f32_16x16x32_bf16 v[126:129], v[130:133], v[162:165], v[126:129]
	v_mfma_f32_16x16x32_bf16 v[122:125], v[138:141], v[162:165], v[122:125]
	v_mfma_f32_16x16x32_bf16 v[110:113], v[130:133], v[170:173], v[110:113]
	v_mfma_f32_16x16x32_bf16 v[106:109], v[138:141], v[170:173], v[106:109]
	v_mfma_f32_16x16x32_bf16 v[94:97], v[130:133], v[178:181], v[94:97]
	v_mfma_f32_16x16x32_bf16 v[90:93], v[138:141], v[178:181], v[90:93]
	v_mfma_f32_16x16x32_bf16 v[78:81], v[130:133], v[186:189], v[78:81]
	v_mfma_f32_16x16x32_bf16 v[74:77], v[138:141], v[186:189], v[74:77]
	v_mfma_f32_16x16x32_bf16 v[126:129], v[134:137], v[166:169], v[126:129]
	v_mfma_f32_16x16x32_bf16 v[122:125], v[142:145], v[166:169], v[122:125]
	v_mfma_f32_16x16x32_bf16 v[110:113], v[134:137], v[174:177], v[110:113]
	v_mfma_f32_16x16x32_bf16 v[106:109], v[142:145], v[174:177], v[106:109]
	v_mfma_f32_16x16x32_bf16 v[94:97], v[134:137], v[182:185], v[94:97]
	v_mfma_f32_16x16x32_bf16 v[90:93], v[142:145], v[182:185], v[90:93]
	v_mfma_f32_16x16x32_bf16 v[78:81], v[134:137], v[190:193], v[78:81]
	v_mfma_f32_16x16x32_bf16 v[74:77], v[142:145], v[190:193], v[74:77]
	s_setprio 0
	s_add_i32 s41, s12, s39
	s_add_u32 s42, s16, 0x40000
	s_addc_u32 s43, s17, 0
	s_setprio 1
	v_mfma_f32_16x16x32_bf16 v[118:121], v[146:149], v[162:165], v[118:121]
	v_mfma_f32_16x16x32_bf16 v[114:117], v[154:157], v[162:165], v[114:117]
	v_mfma_f32_16x16x32_bf16 v[102:105], v[146:149], v[170:173], v[102:105]
	v_mfma_f32_16x16x32_bf16 v[98:101], v[154:157], v[170:173], v[98:101]
	v_mfma_f32_16x16x32_bf16 v[86:89], v[146:149], v[178:181], v[86:89]
	v_mfma_f32_16x16x32_bf16 v[82:85], v[154:157], v[178:181], v[82:85]
	v_mfma_f32_16x16x32_bf16 v[70:73], v[146:149], v[186:189], v[70:73]
	v_mfma_f32_16x16x32_bf16 v[66:69], v[154:157], v[186:189], v[66:69]
	v_mfma_f32_16x16x32_bf16 v[118:121], v[150:153], v[166:169], v[118:121]
	v_mfma_f32_16x16x32_bf16 v[114:117], v[158:161], v[166:169], v[114:117]
	v_mfma_f32_16x16x32_bf16 v[102:105], v[150:153], v[174:177], v[102:105]
	v_mfma_f32_16x16x32_bf16 v[98:101], v[158:161], v[174:177], v[98:101]
	v_mfma_f32_16x16x32_bf16 v[86:89], v[150:153], v[182:185], v[86:89]
	v_mfma_f32_16x16x32_bf16 v[82:85], v[158:161], v[182:185], v[82:85]
	v_mfma_f32_16x16x32_bf16 v[70:73], v[150:153], v[190:193], v[70:73]
	v_mfma_f32_16x16x32_bf16 v[66:69], v[158:161], v[190:193], v[66:69]
	s_setprio 0
	s_barrier
	s_mov_b32 m0, s41
	ds_read_b128 v[162:165], v247 offset:16384
	ds_read_b128 v[166:169], v247 offset:17408
	ds_read_b128 v[170:173], v247 offset:18432
	ds_read_b128 v[174:177], v247 offset:19456
	ds_read_b128 v[178:181], v247 offset:20480
	ds_read_b128 v[182:185], v247 offset:21504
	ds_read_b128 v[186:189], v247 offset:22528
	ds_read_b128 v[190:193], v247 offset:23552
	global_load_lds_dwordx4 v212, s[16:17]
	s_add_i32 m0, s41, 0x2000
	s_add_i32 s41, s13, s39
	global_load_lds_dwordx4 v216, s[16:17]
	s_mov_b32 m0, s41
	s_nop 0
	global_load_lds_dwordx4 v212, s[42:43]
	s_add_i32 m0, s41, 0x2000
	s_nop 0
	global_load_lds_dwordx4 v216, s[42:43]
	s_mov_b32 m0, s71
	s_nop 0
	global_load_lds_dwordx4 v210, s[78:79]
	s_mov_b32 m0, s20
	s_nop 0
	global_load_lds_dwordx4 v214, s[78:79]
	s_waitcnt vmcnt(8)
	s_waitcnt lgkmcnt(0)
	s_barrier
	s_setprio 1
	s_waitcnt lgkmcnt(0)
	v_mfma_f32_16x16x32_bf16 v[62:65], v[130:133], v[162:165], v[62:65]
	v_mfma_f32_16x16x32_bf16 v[58:61], v[138:141], v[162:165], v[58:61]
	v_mfma_f32_16x16x32_bf16 v[46:49], v[130:133], v[170:173], v[46:49]
	v_mfma_f32_16x16x32_bf16 v[42:45], v[138:141], v[170:173], v[42:45]
	v_mfma_f32_16x16x32_bf16 v[30:33], v[130:133], v[178:181], v[30:33]
	v_mfma_f32_16x16x32_bf16 v[26:29], v[138:141], v[178:181], v[26:29]
	v_mfma_f32_16x16x32_bf16 v[14:17], v[130:133], v[186:189], v[14:17]
	v_mfma_f32_16x16x32_bf16 v[10:13], v[138:141], v[186:189], v[10:13]
	v_mfma_f32_16x16x32_bf16 v[62:65], v[134:137], v[166:169], v[62:65]
	v_mfma_f32_16x16x32_bf16 v[58:61], v[142:145], v[166:169], v[58:61]
	v_mfma_f32_16x16x32_bf16 v[46:49], v[134:137], v[174:177], v[46:49]
	v_mfma_f32_16x16x32_bf16 v[42:45], v[142:145], v[174:177], v[42:45]
	v_mfma_f32_16x16x32_bf16 v[30:33], v[134:137], v[182:185], v[30:33]
	v_mfma_f32_16x16x32_bf16 v[26:29], v[142:145], v[182:185], v[26:29]
	v_mfma_f32_16x16x32_bf16 v[14:17], v[134:137], v[190:193], v[14:17]
	v_mfma_f32_16x16x32_bf16 v[10:13], v[142:145], v[190:193], v[10:13]
	s_setprio 0
	s_add_i32 s41, 0, 0x18000
	s_add_i32 s44, 0, 0x1c000
	s_add_u32 s42, s78, 0x40000
	s_addc_u32 s43, s79, 0
	s_setprio 1
	v_mfma_f32_16x16x32_bf16 v[54:57], v[146:149], v[162:165], v[54:57]
	v_mfma_f32_16x16x32_bf16 v[50:53], v[154:157], v[162:165], v[50:53]
	v_mfma_f32_16x16x32_bf16 v[38:41], v[146:149], v[170:173], v[38:41]
	v_mfma_f32_16x16x32_bf16 v[34:37], v[154:157], v[170:173], v[34:37]
	v_mfma_f32_16x16x32_bf16 v[22:25], v[146:149], v[178:181], v[22:25]
	v_mfma_f32_16x16x32_bf16 v[18:21], v[154:157], v[178:181], v[18:21]
	v_mfma_f32_16x16x32_bf16 v[6:9], v[146:149], v[186:189], v[6:9]
	v_mfma_f32_16x16x32_bf16 v[2:5], v[154:157], v[186:189], v[2:5]
	v_mfma_f32_16x16x32_bf16 v[54:57], v[150:153], v[166:169], v[54:57]
	v_mfma_f32_16x16x32_bf16 v[50:53], v[158:161], v[166:169], v[50:53]
	v_mfma_f32_16x16x32_bf16 v[38:41], v[150:153], v[174:177], v[38:41]
	v_mfma_f32_16x16x32_bf16 v[34:37], v[158:161], v[174:177], v[34:37]
	v_mfma_f32_16x16x32_bf16 v[22:25], v[150:153], v[182:185], v[22:25]
	v_mfma_f32_16x16x32_bf16 v[18:21], v[158:161], v[182:185], v[18:21]
	v_mfma_f32_16x16x32_bf16 v[6:9], v[150:153], v[190:193], v[6:9]
	v_mfma_f32_16x16x32_bf16 v[2:5], v[158:161], v[190:193], v[2:5]
	s_setprio 0
	s_barrier
	v_add_u32_e32 v142, s41, v223
	v_add_u32_e32 v158, s44, v223
	ds_read_b128 v[130:133], v142
	ds_read_b128 v[134:137], v142 offset:1024
	ds_read_b128 v[138:141], v142 offset:2048
	ds_read_b128 v[142:145], v142 offset:3072
	ds_read_b128 v[146:149], v158
	ds_read_b128 v[150:153], v158 offset:1024
	ds_read_b128 v[154:157], v158 offset:2048
	ds_read_b128 v[158:161], v158 offset:3072
	s_mov_b32 m0, s21
	ds_read_b128 v[162:165], v247 offset:32768
	ds_read_b128 v[166:169], v247 offset:33792
	ds_read_b128 v[170:173], v247 offset:34816
	ds_read_b128 v[174:177], v247 offset:35840
	ds_read_b128 v[178:181], v247 offset:36864
	ds_read_b128 v[182:185], v247 offset:37888
	ds_read_b128 v[186:189], v247 offset:38912
	ds_read_b128 v[190:193], v247 offset:39936
	global_load_lds_dwordx4 v210, s[42:43]
	s_mov_b32 m0, s22
	s_nop 0
	global_load_lds_dwordx4 v214, s[42:43]
	s_waitcnt vmcnt(8)
	s_waitcnt lgkmcnt(0)
	s_barrier
	s_setprio 1
	s_waitcnt lgkmcnt(0)
	v_mfma_f32_16x16x32_bf16 v[126:129], v[130:133], v[162:165], v[126:129]
	v_mfma_f32_16x16x32_bf16 v[122:125], v[138:141], v[162:165], v[122:125]
	v_mfma_f32_16x16x32_bf16 v[110:113], v[130:133], v[170:173], v[110:113]
	v_mfma_f32_16x16x32_bf16 v[106:109], v[138:141], v[170:173], v[106:109]
	v_mfma_f32_16x16x32_bf16 v[94:97], v[130:133], v[178:181], v[94:97]
	v_mfma_f32_16x16x32_bf16 v[90:93], v[138:141], v[178:181], v[90:93]
	v_mfma_f32_16x16x32_bf16 v[78:81], v[130:133], v[186:189], v[78:81]
	v_mfma_f32_16x16x32_bf16 v[74:77], v[138:141], v[186:189], v[74:77]
	v_mfma_f32_16x16x32_bf16 v[126:129], v[134:137], v[166:169], v[126:129]
	v_mfma_f32_16x16x32_bf16 v[122:125], v[142:145], v[166:169], v[122:125]
	v_mfma_f32_16x16x32_bf16 v[110:113], v[134:137], v[174:177], v[110:113]
	v_mfma_f32_16x16x32_bf16 v[106:109], v[142:145], v[174:177], v[106:109]
	v_mfma_f32_16x16x32_bf16 v[94:97], v[134:137], v[182:185], v[94:97]
	v_mfma_f32_16x16x32_bf16 v[90:93], v[142:145], v[182:185], v[90:93]
	v_mfma_f32_16x16x32_bf16 v[78:81], v[134:137], v[190:193], v[78:81]
	v_mfma_f32_16x16x32_bf16 v[74:77], v[142:145], v[190:193], v[74:77]
	s_setprio 0
	s_add_i32 s41, s41, s39
	s_setprio 1
	v_mfma_f32_16x16x32_bf16 v[118:121], v[146:149], v[162:165], v[118:121]
	v_mfma_f32_16x16x32_bf16 v[114:117], v[154:157], v[162:165], v[114:117]
	v_mfma_f32_16x16x32_bf16 v[102:105], v[146:149], v[170:173], v[102:105]
	v_mfma_f32_16x16x32_bf16 v[98:101], v[154:157], v[170:173], v[98:101]
	v_mfma_f32_16x16x32_bf16 v[86:89], v[146:149], v[178:181], v[86:89]
	v_mfma_f32_16x16x32_bf16 v[82:85], v[154:157], v[178:181], v[82:85]
	v_mfma_f32_16x16x32_bf16 v[70:73], v[146:149], v[186:189], v[70:73]
	v_mfma_f32_16x16x32_bf16 v[66:69], v[154:157], v[186:189], v[66:69]
	v_mfma_f32_16x16x32_bf16 v[118:121], v[150:153], v[166:169], v[118:121]
	v_mfma_f32_16x16x32_bf16 v[114:117], v[158:161], v[166:169], v[114:117]
	v_mfma_f32_16x16x32_bf16 v[102:105], v[150:153], v[174:177], v[102:105]
	v_mfma_f32_16x16x32_bf16 v[98:101], v[158:161], v[174:177], v[98:101]
	v_mfma_f32_16x16x32_bf16 v[86:89], v[150:153], v[182:185], v[86:89]
	v_mfma_f32_16x16x32_bf16 v[82:85], v[158:161], v[182:185], v[82:85]
	v_mfma_f32_16x16x32_bf16 v[70:73], v[150:153], v[190:193], v[70:73]
	v_mfma_f32_16x16x32_bf16 v[66:69], v[158:161], v[190:193], v[66:69]
	s_setprio 0
	s_barrier
	s_add_i32 m0, s41, 0xffffff80
	ds_read_b128 v[162:165], v247 offset:49152
	ds_read_b128 v[166:169], v247 offset:50176
	ds_read_b128 v[170:173], v247 offset:51200
	ds_read_b128 v[174:177], v247 offset:52224
	ds_read_b128 v[178:181], v247 offset:53248
	ds_read_b128 v[182:185], v247 offset:54272
	ds_read_b128 v[186:189], v247 offset:55296
	ds_read_b128 v[190:193], v247 offset:56320
	global_load_lds_dwordx4 v212, s[16:17] offset:128
	s_add_i32 m0, s41, 0x1f80
	s_add_i32 s41, s44, s39
	global_load_lds_dwordx4 v216, s[16:17] offset:128
	s_add_u32 s16, s16, 0x40080
	s_addc_u32 s17, s17, 0
	s_mov_b32 m0, s41
	s_nop 0
	global_load_lds_dwordx4 v212, s[16:17]
	s_add_i32 m0, s41, 0x2000
	s_nop 0
	global_load_lds_dwordx4 v216, s[16:17]
	s_add_i32 m0, s14, 0xffffff80
	s_nop 0
	global_load_lds_dwordx4 v210, s[78:79] offset:128
	s_add_i32 m0, s15, 0xffffff80
	s_nop 0
	global_load_lds_dwordx4 v214, s[78:79] offset:128
	s_waitcnt vmcnt(8)
	s_waitcnt lgkmcnt(0)
	s_barrier
	s_setprio 1
	s_waitcnt lgkmcnt(0)
	v_mfma_f32_16x16x32_bf16 v[62:65], v[130:133], v[162:165], v[62:65]
	v_mfma_f32_16x16x32_bf16 v[58:61], v[138:141], v[162:165], v[58:61]
	v_mfma_f32_16x16x32_bf16 v[46:49], v[130:133], v[170:173], v[46:49]
	v_mfma_f32_16x16x32_bf16 v[42:45], v[138:141], v[170:173], v[42:45]
	v_mfma_f32_16x16x32_bf16 v[30:33], v[130:133], v[178:181], v[30:33]
	v_mfma_f32_16x16x32_bf16 v[26:29], v[138:141], v[178:181], v[26:29]
	v_mfma_f32_16x16x32_bf16 v[14:17], v[130:133], v[186:189], v[14:17]
	v_mfma_f32_16x16x32_bf16 v[10:13], v[138:141], v[186:189], v[10:13]
	v_mfma_f32_16x16x32_bf16 v[62:65], v[134:137], v[166:169], v[62:65]
	v_mfma_f32_16x16x32_bf16 v[58:61], v[142:145], v[166:169], v[58:61]
	v_mfma_f32_16x16x32_bf16 v[46:49], v[134:137], v[174:177], v[46:49]
	v_mfma_f32_16x16x32_bf16 v[42:45], v[142:145], v[174:177], v[42:45]
	v_mfma_f32_16x16x32_bf16 v[30:33], v[134:137], v[182:185], v[30:33]
	v_mfma_f32_16x16x32_bf16 v[26:29], v[142:145], v[182:185], v[26:29]
	v_mfma_f32_16x16x32_bf16 v[14:17], v[134:137], v[190:193], v[14:17]
	v_mfma_f32_16x16x32_bf16 v[10:13], v[142:145], v[190:193], v[10:13]
	s_setprio 0
	s_add_i32 s40, s40, 2
	s_add_u32 s6, s6, 0x100
	s_addc_u32 s7, s7, 0
	s_add_u32 s35, s35, 0x100
	s_addc_u32 s37, s37, 0
	s_setprio 1
	v_mfma_f32_16x16x32_bf16 v[54:57], v[146:149], v[162:165], v[54:57]
	v_mfma_f32_16x16x32_bf16 v[50:53], v[154:157], v[162:165], v[50:53]
	v_mfma_f32_16x16x32_bf16 v[38:41], v[146:149], v[170:173], v[38:41]
	v_mfma_f32_16x16x32_bf16 v[34:37], v[154:157], v[170:173], v[34:37]
	v_mfma_f32_16x16x32_bf16 v[22:25], v[146:149], v[178:181], v[22:25]
	v_mfma_f32_16x16x32_bf16 v[18:21], v[154:157], v[178:181], v[18:21]
	v_mfma_f32_16x16x32_bf16 v[6:9], v[146:149], v[186:189], v[6:9]
	v_mfma_f32_16x16x32_bf16 v[2:5], v[154:157], v[186:189], v[2:5]
	v_mfma_f32_16x16x32_bf16 v[54:57], v[150:153], v[166:169], v[54:57]
	v_mfma_f32_16x16x32_bf16 v[50:53], v[158:161], v[166:169], v[50:53]
	v_mfma_f32_16x16x32_bf16 v[38:41], v[150:153], v[174:177], v[38:41]
	v_mfma_f32_16x16x32_bf16 v[34:37], v[158:161], v[174:177], v[34:37]
	v_mfma_f32_16x16x32_bf16 v[22:25], v[150:153], v[182:185], v[22:25]
	v_mfma_f32_16x16x32_bf16 v[18:21], v[158:161], v[182:185], v[18:21]
	v_mfma_f32_16x16x32_bf16 v[6:9], v[150:153], v[190:193], v[6:9]
	v_mfma_f32_16x16x32_bf16 v[2:5], v[158:161], v[190:193], v[2:5]
	s_setprio 0
	s_barrier
	s_cmp_gt_u32 s40, 13
	s_cbranch_scc0 .LBB0_120
	s_and_b64 vcc, exec, s[48:49]
	s_cbranch_vccz .LBB0_123
	s_barrier

.LBB0_518:
	ds_read_b128 v[148:151], v143
	ds_read_b128 v[152:155], v143 offset:1024
	ds_read_b128 v[158:161], v143 offset:2048
	ds_read_b128 v[162:165], v143 offset:3072
	ds_read_b128 v[166:169], v144
	ds_read_b128 v[170:173], v144 offset:1024
	ds_read_b128 v[174:177], v144 offset:2048
	ds_read_b128 v[178:181], v144 offset:3072
	s_add_u32 s16, s8, s10
	s_addc_u32 s17, s9, s11
	s_add_u32 s16, s16, 0x1000100
	s_addc_u32 s17, s17, 0
	s_add_u32 s44, s30, s10
	s_addc_u32 s45, s31, s11
	s_cmpk_eq_i32 s10, 0x700
	s_cselect_b32 s29, s7, s17
	s_cselect_b32 s28, s6, s16
	s_cselect_b32 s17, s5, s45
	s_cselect_b32 s16, s4, s44
	s_mov_b32 m0, s34
	v_lshl_add_u64 v[214:215], v[138:139], 0, s[10:11]
	ds_read_b128 v[182:185], v145
	ds_read_b128 v[186:189], v145 offset:1024
	ds_read_b128 v[190:193], v145 offset:2048
	ds_read_b128 v[194:197], v145 offset:3072
	ds_read_b128 v[198:201], v145 offset:4096
	ds_read_b128 v[202:205], v145 offset:5120
	ds_read_b128 v[206:209], v145 offset:6144
	ds_read_b128 v[210:213], v145 offset:7168
	global_load_lds_dwordx4 v[214:215], off
	v_lshl_add_u64 v[214:215], v[140:141], 0, s[10:11]
	s_mov_b32 m0, s35
	s_nop 0
	global_load_lds_dwordx4 v[214:215], off
	s_waitcnt vmcnt(8)
	s_waitcnt lgkmcnt(0)
	s_barrier
	s_setprio 1
	s_waitcnt lgkmcnt(0)
	v_mfma_f32_16x16x32_bf16 v[126:129], v[148:151], v[182:185], v[126:129]
	v_mfma_f32_16x16x32_bf16 v[122:125], v[158:161], v[182:185], v[122:125]
	v_mfma_f32_16x16x32_bf16 v[110:113], v[148:151], v[190:193], v[110:113]
	v_mfma_f32_16x16x32_bf16 v[106:109], v[158:161], v[190:193], v[106:109]
	v_mfma_f32_16x16x32_bf16 v[94:97], v[148:151], v[198:201], v[94:97]
	v_mfma_f32_16x16x32_bf16 v[90:93], v[158:161], v[198:201], v[90:93]
	v_mfma_f32_16x16x32_bf16 v[78:81], v[148:151], v[206:209], v[78:81]
	v_mfma_f32_16x16x32_bf16 v[74:77], v[158:161], v[206:209], v[74:77]
	v_mfma_f32_16x16x32_bf16 v[126:129], v[152:155], v[186:189], v[126:129]
	v_mfma_f32_16x16x32_bf16 v[122:125], v[162:165], v[186:189], v[122:125]
	v_mfma_f32_16x16x32_bf16 v[110:113], v[152:155], v[194:197], v[110:113]
	v_mfma_f32_16x16x32_bf16 v[106:109], v[162:165], v[194:197], v[106:109]
	v_mfma_f32_16x16x32_bf16 v[94:97], v[152:155], v[202:205], v[94:97]
	v_mfma_f32_16x16x32_bf16 v[90:93], v[162:165], v[202:205], v[90:93]
	v_mfma_f32_16x16x32_bf16 v[78:81], v[152:155], v[210:213], v[78:81]
	v_mfma_f32_16x16x32_bf16 v[74:77], v[162:165], v[210:213], v[74:77]
	s_setprio 0
	s_add_u32 s44, s16, 0x40000
	s_addc_u32 s45, s17, 0
	s_setprio 1
	v_mfma_f32_16x16x32_bf16 v[118:121], v[166:169], v[182:185], v[118:121]
	v_mfma_f32_16x16x32_bf16 v[114:117], v[174:177], v[182:185], v[114:117]
	v_mfma_f32_16x16x32_bf16 v[102:105], v[166:169], v[190:193], v[102:105]
	v_mfma_f32_16x16x32_bf16 v[98:101], v[174:177], v[190:193], v[98:101]
	v_mfma_f32_16x16x32_bf16 v[86:89], v[166:169], v[198:201], v[86:89]
	v_mfma_f32_16x16x32_bf16 v[82:85], v[174:177], v[198:201], v[82:85]
	v_mfma_f32_16x16x32_bf16 v[70:73], v[166:169], v[206:209], v[70:73]
	v_mfma_f32_16x16x32_bf16 v[66:69], v[174:177], v[206:209], v[66:69]
	v_mfma_f32_16x16x32_bf16 v[118:121], v[170:173], v[186:189], v[118:121]
	v_mfma_f32_16x16x32_bf16 v[114:117], v[178:181], v[186:189], v[114:117]
	v_mfma_f32_16x16x32_bf16 v[102:105], v[170:173], v[194:197], v[102:105]
	v_mfma_f32_16x16x32_bf16 v[98:101], v[178:181], v[194:197], v[98:101]
	v_mfma_f32_16x16x32_bf16 v[86:89], v[170:173], v[202:205], v[86:89]
	v_mfma_f32_16x16x32_bf16 v[82:85], v[178:181], v[202:205], v[82:85]
	v_mfma_f32_16x16x32_bf16 v[70:73], v[170:173], v[210:213], v[70:73]
	v_mfma_f32_16x16x32_bf16 v[66:69], v[178:181], v[210:213], v[66:69]
	s_setprio 0
	s_barrier
	s_mov_b32 m0, s36
	v_lshl_add_u64 v[214:215], s[16:17], 0, v[132:133]
	ds_read_b128 v[182:185], v145 offset:16384
	ds_read_b128 v[186:189], v145 offset:17408
	ds_read_b128 v[190:193], v145 offset:18432
	ds_read_b128 v[194:197], v145 offset:19456
	ds_read_b128 v[198:201], v145 offset:20480
	ds_read_b128 v[202:205], v145 offset:21504
	ds_read_b128 v[206:209], v145 offset:22528
	ds_read_b128 v[210:213], v145 offset:23552
	global_load_lds_dwordx4 v132, s[16:17]
	v_lshl_add_u64 v[216:217], s[16:17], 0, v[136:137]
	s_mov_b32 m0, s37
	global_load_lds_dwordx4 v136, s[16:17]
	s_mov_b32 m0, s38
	v_lshl_add_u64 v[220:221], s[28:29], 0, v[134:135]
	global_load_lds_dwordx4 v132, s[44:45]
	s_mov_b32 m0, s39
	s_nop 0
	global_load_lds_dwordx4 v136, s[44:45]
	v_lshl_add_u64 v[218:219], s[28:29], 0, v[130:131]
	s_mov_b32 m0, s1
	s_nop 0
	global_load_lds_dwordx4 v130, s[28:29]
	s_mov_b32 m0, s15
	s_nop 0
	global_load_lds_dwordx4 v134, s[28:29]
	s_waitcnt vmcnt(8)
	s_waitcnt lgkmcnt(0)
	s_barrier
	s_setprio 1
	s_waitcnt lgkmcnt(0)
	v_mfma_f32_16x16x32_bf16 v[62:65], v[148:151], v[182:185], v[62:65]
	v_mfma_f32_16x16x32_bf16 v[58:61], v[158:161], v[182:185], v[58:61]
	v_mfma_f32_16x16x32_bf16 v[46:49], v[148:151], v[190:193], v[46:49]
	v_mfma_f32_16x16x32_bf16 v[42:45], v[158:161], v[190:193], v[42:45]
	v_mfma_f32_16x16x32_bf16 v[30:33], v[148:151], v[198:201], v[30:33]
	v_mfma_f32_16x16x32_bf16 v[26:29], v[158:161], v[198:201], v[26:29]
	v_mfma_f32_16x16x32_bf16 v[14:17], v[148:151], v[206:209], v[14:17]
	v_mfma_f32_16x16x32_bf16 v[10:13], v[158:161], v[206:209], v[10:13]
	v_mfma_f32_16x16x32_bf16 v[62:65], v[152:155], v[186:189], v[62:65]
	v_mfma_f32_16x16x32_bf16 v[58:61], v[162:165], v[186:189], v[58:61]
	v_mfma_f32_16x16x32_bf16 v[46:49], v[152:155], v[194:197], v[46:49]
	v_mfma_f32_16x16x32_bf16 v[42:45], v[162:165], v[194:197], v[42:45]
	v_mfma_f32_16x16x32_bf16 v[30:33], v[152:155], v[202:205], v[30:33]
	v_mfma_f32_16x16x32_bf16 v[26:29], v[162:165], v[202:205], v[26:29]
	v_mfma_f32_16x16x32_bf16 v[14:17], v[152:155], v[210:213], v[14:17]
	v_mfma_f32_16x16x32_bf16 v[10:13], v[162:165], v[210:213], v[10:13]
	s_setprio 0
	s_add_u32 s28, s28, 0x40000
	s_addc_u32 s29, s29, 0
	s_setprio 1
	v_mfma_f32_16x16x32_bf16 v[54:57], v[166:169], v[182:185], v[54:57]
	v_mfma_f32_16x16x32_bf16 v[50:53], v[174:177], v[182:185], v[50:53]
	v_mfma_f32_16x16x32_bf16 v[38:41], v[166:169], v[190:193], v[38:41]
	v_mfma_f32_16x16x32_bf16 v[34:37], v[174:177], v[190:193], v[34:37]
	v_mfma_f32_16x16x32_bf16 v[22:25], v[166:169], v[198:201], v[22:25]
	v_mfma_f32_16x16x32_bf16 v[18:21], v[174:177], v[198:201], v[18:21]
	v_mfma_f32_16x16x32_bf16 v[6:9], v[166:169], v[206:209], v[6:9]
	v_mfma_f32_16x16x32_bf16 v[2:5], v[174:177], v[206:209], v[2:5]
	v_mfma_f32_16x16x32_bf16 v[54:57], v[170:173], v[186:189], v[54:57]
	v_mfma_f32_16x16x32_bf16 v[50:53], v[178:181], v[186:189], v[50:53]
	v_mfma_f32_16x16x32_bf16 v[38:41], v[170:173], v[194:197], v[38:41]
	v_mfma_f32_16x16x32_bf16 v[34:37], v[178:181], v[194:197], v[34:37]
	v_mfma_f32_16x16x32_bf16 v[22:25], v[170:173], v[202:205], v[22:25]
	v_mfma_f32_16x16x32_bf16 v[18:21], v[178:181], v[202:205], v[18:21]
	v_mfma_f32_16x16x32_bf16 v[6:9], v[170:173], v[210:213], v[6:9]
	v_mfma_f32_16x16x32_bf16 v[2:5], v[178:181], v[210:213], v[2:5]
	s_setprio 0
	s_barrier
	ds_read_b128 v[148:151], v146
	ds_read_b128 v[152:155], v146 offset:1024
	ds_read_b128 v[158:161], v146 offset:2048
	ds_read_b128 v[162:165], v146 offset:3072
	ds_read_b128 v[166:169], v147
	ds_read_b128 v[170:173], v147 offset:1024
	ds_read_b128 v[174:177], v147 offset:2048
	ds_read_b128 v[178:181], v147 offset:3072
	s_mov_b32 m0, s20
	ds_read_b128 v[182:185], v145 offset:32768
	ds_read_b128 v[186:189], v145 offset:33792
	ds_read_b128 v[190:193], v145 offset:34816
	ds_read_b128 v[194:197], v145 offset:35840
	ds_read_b128 v[198:201], v145 offset:36864
	ds_read_b128 v[202:205], v145 offset:37888
	ds_read_b128 v[206:209], v145 offset:38912
	ds_read_b128 v[210:213], v145 offset:39936
	global_load_lds_dwordx4 v130, s[28:29]
	s_mov_b32 m0, s21
	s_nop 0
	global_load_lds_dwordx4 v134, s[28:29]
	s_waitcnt vmcnt(8)
	s_waitcnt lgkmcnt(0)
	s_barrier
	s_setprio 1
	s_waitcnt lgkmcnt(0)
	v_mfma_f32_16x16x32_bf16 v[126:129], v[148:151], v[182:185], v[126:129]
	v_mfma_f32_16x16x32_bf16 v[122:125], v[158:161], v[182:185], v[122:125]
	v_mfma_f32_16x16x32_bf16 v[110:113], v[148:151], v[190:193], v[110:113]
	v_mfma_f32_16x16x32_bf16 v[106:109], v[158:161], v[190:193], v[106:109]
	v_mfma_f32_16x16x32_bf16 v[94:97], v[148:151], v[198:201], v[94:97]
	v_mfma_f32_16x16x32_bf16 v[90:93], v[158:161], v[198:201], v[90:93]
	v_mfma_f32_16x16x32_bf16 v[78:81], v[148:151], v[206:209], v[78:81]
	v_mfma_f32_16x16x32_bf16 v[74:77], v[158:161], v[206:209], v[74:77]
	v_mfma_f32_16x16x32_bf16 v[126:129], v[152:155], v[186:189], v[126:129]
	v_mfma_f32_16x16x32_bf16 v[122:125], v[162:165], v[186:189], v[122:125]
	v_mfma_f32_16x16x32_bf16 v[110:113], v[152:155], v[194:197], v[110:113]
	v_mfma_f32_16x16x32_bf16 v[106:109], v[162:165], v[194:197], v[106:109]
	v_mfma_f32_16x16x32_bf16 v[94:97], v[152:155], v[202:205], v[94:97]
	v_mfma_f32_16x16x32_bf16 v[90:93], v[162:165], v[202:205], v[90:93]
	v_mfma_f32_16x16x32_bf16 v[78:81], v[152:155], v[210:213], v[78:81]
	v_mfma_f32_16x16x32_bf16 v[74:77], v[162:165], v[210:213], v[74:77]
	s_setprio 0
	s_add_u32 s16, s16, 0x40080
	s_addc_u32 s17, s17, 0
	s_setprio 1
	v_mfma_f32_16x16x32_bf16 v[118:121], v[166:169], v[182:185], v[118:121]
	v_mfma_f32_16x16x32_bf16 v[114:117], v[174:177], v[182:185], v[114:117]
	v_mfma_f32_16x16x32_bf16 v[102:105], v[166:169], v[190:193], v[102:105]
	v_mfma_f32_16x16x32_bf16 v[98:101], v[174:177], v[190:193], v[98:101]
	v_mfma_f32_16x16x32_bf16 v[86:89], v[166:169], v[198:201], v[86:89]
	v_mfma_f32_16x16x32_bf16 v[82:85], v[174:177], v[198:201], v[82:85]
	v_mfma_f32_16x16x32_bf16 v[70:73], v[166:169], v[206:209], v[70:73]
	v_mfma_f32_16x16x32_bf16 v[66:69], v[174:177], v[206:209], v[66:69]
	v_mfma_f32_16x16x32_bf16 v[118:121], v[170:173], v[186:189], v[118:121]
	v_mfma_f32_16x16x32_bf16 v[114:117], v[178:181], v[186:189], v[114:117]
	v_mfma_f32_16x16x32_bf16 v[102:105], v[170:173], v[194:197], v[102:105]
	v_mfma_f32_16x16x32_bf16 v[98:101], v[178:181], v[194:197], v[98:101]
	v_mfma_f32_16x16x32_bf16 v[86:89], v[170:173], v[202:205], v[86:89]
	v_mfma_f32_16x16x32_bf16 v[82:85], v[178:181], v[202:205], v[82:85]
	v_mfma_f32_16x16x32_bf16 v[70:73], v[170:173], v[210:213], v[70:73]
	v_mfma_f32_16x16x32_bf16 v[66:69], v[178:181], v[210:213], v[66:69]
	s_setprio 0
	s_barrier
	s_mov_b32 m0, s40
	v_lshl_add_u64 v[214:215], v[214:215], 0, s[2:3]
	ds_read_b128 v[182:185], v145 offset:49152
	ds_read_b128 v[186:189], v145 offset:50176
	ds_read_b128 v[190:193], v145 offset:51200
	ds_read_b128 v[194:197], v145 offset:52224
	ds_read_b128 v[198:201], v145 offset:53248
	ds_read_b128 v[202:205], v145 offset:54272
	ds_read_b128 v[206:209], v145 offset:55296
	ds_read_b128 v[210:213], v145 offset:56320
	global_load_lds_dwordx4 v[214:215], off
	v_lshl_add_u64 v[214:215], v[216:217], 0, s[2:3]
	s_mov_b32 m0, s41
	global_load_lds_dwordx4 v[214:215], off
	s_mov_b32 m0, s42
	s_nop 0
	global_load_lds_dwordx4 v132, s[16:17]
	s_mov_b32 m0, s43
	s_nop 0
	global_load_lds_dwordx4 v136, s[16:17]
	v_lshl_add_u64 v[214:215], v[218:219], 0, s[2:3]
	s_mov_b32 m0, s22
	s_nop 0
	global_load_lds_dwordx4 v[214:215], off
	v_lshl_add_u64 v[214:215], v[220:221], 0, s[2:3]
	s_mov_b32 m0, s23
	s_nop 0
	global_load_lds_dwordx4 v[214:215], off
	s_waitcnt vmcnt(8)
	s_waitcnt lgkmcnt(0)
	s_barrier
	s_setprio 1
	s_waitcnt lgkmcnt(0)
	v_mfma_f32_16x16x32_bf16 v[62:65], v[148:151], v[182:185], v[62:65]
	v_mfma_f32_16x16x32_bf16 v[58:61], v[158:161], v[182:185], v[58:61]
	v_mfma_f32_16x16x32_bf16 v[46:49], v[148:151], v[190:193], v[46:49]
	v_mfma_f32_16x16x32_bf16 v[42:45], v[158:161], v[190:193], v[42:45]
	v_mfma_f32_16x16x32_bf16 v[30:33], v[148:151], v[198:201], v[30:33]
	v_mfma_f32_16x16x32_bf16 v[26:29], v[158:161], v[198:201], v[26:29]
	v_mfma_f32_16x16x32_bf16 v[14:17], v[148:151], v[206:209], v[14:17]
	v_mfma_f32_16x16x32_bf16 v[10:13], v[158:161], v[206:209], v[10:13]
	v_mfma_f32_16x16x32_bf16 v[62:65], v[152:155], v[186:189], v[62:65]
	v_mfma_f32_16x16x32_bf16 v[58:61], v[162:165], v[186:189], v[58:61]
	v_mfma_f32_16x16x32_bf16 v[46:49], v[152:155], v[194:197], v[46:49]
	v_mfma_f32_16x16x32_bf16 v[42:45], v[162:165], v[194:197], v[42:45]
	v_mfma_f32_16x16x32_bf16 v[30:33], v[152:155], v[202:205], v[30:33]
	v_mfma_f32_16x16x32_bf16 v[26:29], v[162:165], v[202:205], v[26:29]
	v_mfma_f32_16x16x32_bf16 v[14:17], v[152:155], v[210:213], v[14:17]
	v_mfma_f32_16x16x32_bf16 v[10:13], v[162:165], v[210:213], v[10:13]
	s_setprio 0
	s_add_i32 s33, s33, 2
	s_add_u32 s10, s10, 0x100
	s_addc_u32 s11, s11, 0
	s_setprio 1
	v_mfma_f32_16x16x32_bf16 v[54:57], v[166:169], v[182:185], v[54:57]
	v_mfma_f32_16x16x32_bf16 v[50:53], v[174:177], v[182:185], v[50:53]
	v_mfma_f32_16x16x32_bf16 v[38:41], v[166:169], v[190:193], v[38:41]
	v_mfma_f32_16x16x32_bf16 v[34:37], v[174:177], v[190:193], v[34:37]
	v_mfma_f32_16x16x32_bf16 v[22:25], v[166:169], v[198:201], v[22:25]
	v_mfma_f32_16x16x32_bf16 v[18:21], v[174:177], v[198:201], v[18:21]
	v_mfma_f32_16x16x32_bf16 v[6:9], v[166:169], v[206:209], v[6:9]
	v_mfma_f32_16x16x32_bf16 v[2:5], v[174:177], v[206:209], v[2:5]
	v_mfma_f32_16x16x32_bf16 v[54:57], v[170:173], v[186:189], v[54:57]
	v_mfma_f32_16x16x32_bf16 v[50:53], v[178:181], v[186:189], v[50:53]
	v_mfma_f32_16x16x32_bf16 v[38:41], v[170:173], v[194:197], v[38:41]
	v_mfma_f32_16x16x32_bf16 v[34:37], v[178:181], v[194:197], v[34:37]
	v_mfma_f32_16x16x32_bf16 v[22:25], v[170:173], v[202:205], v[22:25]
	v_mfma_f32_16x16x32_bf16 v[18:21], v[178:181], v[202:205], v[18:21]
	v_mfma_f32_16x16x32_bf16 v[6:9], v[170:173], v[210:213], v[6:9]
	v_mfma_f32_16x16x32_bf16 v[2:5], v[178:181], v[210:213], v[2:5]
	s_setprio 0
	s_barrier
	s_cmp_gt_u32 s33, 13
	s_cbranch_scc0 .LBB0_518
	s_cmpk_lt_u32 s14, 0x100
	s_cbranch_scc0 .LBB0_521
	s_barrier

.LBB0_1250:
	ds_read_b128 v[146:149], v140
	ds_read_b128 v[150:153], v140 offset:1024
	ds_read_b128 v[154:157], v140 offset:2048
	ds_read_b128 v[158:161], v140 offset:3072
	ds_read_b128 v[162:165], v141
	ds_read_b128 v[166:169], v141 offset:1024
	ds_read_b128 v[170:173], v141 offset:2048
	ds_read_b128 v[174:177], v141 offset:3072
	s_add_u32 s14, s10, s12
	s_addc_u32 s15, s11, s13
	s_add_u32 s14, s14, 0x11400100
	s_addc_u32 s15, s15, 0
	s_add_u32 s39, s1, s12
	s_addc_u32 s40, s26, s13
	s_cmpk_eq_i32 s12, 0x700
	s_cselect_b32 s17, s9, s15
	s_cselect_b32 s16, s8, s14
	s_cselect_b32 s15, s7, s40
	s_cselect_b32 s14, s6, s39
	s_mov_b32 m0, s28
	v_lshl_add_u64 v[210:211], v[134:135], 0, s[12:13]
	ds_read_b128 v[178:181], v142
	ds_read_b128 v[182:185], v142 offset:1024
	ds_read_b128 v[186:189], v142 offset:2048
	ds_read_b128 v[190:193], v142 offset:3072
	ds_read_b128 v[194:197], v142 offset:4096
	ds_read_b128 v[198:201], v142 offset:5120
	ds_read_b128 v[202:205], v142 offset:6144
	ds_read_b128 v[206:209], v142 offset:7168
	global_load_lds_dwordx4 v[210:211], off
	v_lshl_add_u64 v[210:211], v[136:137], 0, s[12:13]
	s_mov_b32 m0, s29
	s_nop 0
	global_load_lds_dwordx4 v[210:211], off
	s_waitcnt vmcnt(8)
	s_waitcnt lgkmcnt(0)
	s_barrier
	s_setprio 1
	s_waitcnt lgkmcnt(0)
	v_mfma_f32_16x16x32_bf16 v[126:129], v[146:149], v[178:181], v[126:129]
	v_mfma_f32_16x16x32_bf16 v[122:125], v[154:157], v[178:181], v[122:125]
	v_mfma_f32_16x16x32_bf16 v[118:121], v[146:149], v[186:189], v[118:121]
	v_mfma_f32_16x16x32_bf16 v[114:117], v[154:157], v[186:189], v[114:117]
	v_mfma_f32_16x16x32_bf16 v[106:109], v[146:149], v[194:197], v[106:109]
	v_mfma_f32_16x16x32_bf16 v[98:101], v[154:157], v[194:197], v[98:101]
	v_mfma_f32_16x16x32_bf16 v[82:85], v[146:149], v[202:205], v[82:85]
	v_mfma_f32_16x16x32_bf16 v[74:77], v[154:157], v[202:205], v[74:77]
	v_mfma_f32_16x16x32_bf16 v[126:129], v[150:153], v[182:185], v[126:129]
	v_mfma_f32_16x16x32_bf16 v[122:125], v[158:161], v[182:185], v[122:125]
	v_mfma_f32_16x16x32_bf16 v[118:121], v[150:153], v[190:193], v[118:121]
	v_mfma_f32_16x16x32_bf16 v[114:117], v[158:161], v[190:193], v[114:117]
	v_mfma_f32_16x16x32_bf16 v[106:109], v[150:153], v[198:201], v[106:109]
	v_mfma_f32_16x16x32_bf16 v[98:101], v[158:161], v[198:201], v[98:101]
	v_mfma_f32_16x16x32_bf16 v[82:85], v[150:153], v[206:209], v[82:85]
	v_mfma_f32_16x16x32_bf16 v[74:77], v[158:161], v[206:209], v[74:77]
	s_setprio 0
	s_add_u32 s40, s14, 0x40000
	s_addc_u32 s41, s15, 0
	s_setprio 1
	v_mfma_f32_16x16x32_bf16 v[110:113], v[162:165], v[178:181], v[110:113]
	v_mfma_f32_16x16x32_bf16 v[102:105], v[170:173], v[178:181], v[102:105]
	v_mfma_f32_16x16x32_bf16 v[94:97], v[162:165], v[186:189], v[94:97]
	v_mfma_f32_16x16x32_bf16 v[90:93], v[170:173], v[186:189], v[90:93]
	v_mfma_f32_16x16x32_bf16 v[86:89], v[162:165], v[194:197], v[86:89]
	v_mfma_f32_16x16x32_bf16 v[78:81], v[170:173], v[194:197], v[78:81]
	v_mfma_f32_16x16x32_bf16 v[70:73], v[162:165], v[202:205], v[70:73]
	v_mfma_f32_16x16x32_bf16 v[66:69], v[170:173], v[202:205], v[66:69]
	v_mfma_f32_16x16x32_bf16 v[110:113], v[166:169], v[182:185], v[110:113]
	v_mfma_f32_16x16x32_bf16 v[102:105], v[174:177], v[182:185], v[102:105]
	v_mfma_f32_16x16x32_bf16 v[94:97], v[166:169], v[190:193], v[94:97]
	v_mfma_f32_16x16x32_bf16 v[90:93], v[174:177], v[190:193], v[90:93]
	v_mfma_f32_16x16x32_bf16 v[86:89], v[166:169], v[198:201], v[86:89]
	v_mfma_f32_16x16x32_bf16 v[78:81], v[174:177], v[198:201], v[78:81]
	v_mfma_f32_16x16x32_bf16 v[70:73], v[166:169], v[206:209], v[70:73]
	v_mfma_f32_16x16x32_bf16 v[66:69], v[174:177], v[206:209], v[66:69]
	s_setprio 0
	s_barrier
	s_mov_b32 m0, s30
	v_lshl_add_u64 v[210:211], s[14:15], 0, v[130:131]
	ds_read_b128 v[178:181], v142 offset:16384
	ds_read_b128 v[182:185], v142 offset:17408
	ds_read_b128 v[186:189], v142 offset:18432
	ds_read_b128 v[190:193], v142 offset:19456
	ds_read_b128 v[194:197], v142 offset:20480
	ds_read_b128 v[198:201], v142 offset:21504
	ds_read_b128 v[202:205], v142 offset:22528
	ds_read_b128 v[206:209], v142 offset:23552
	global_load_lds_dwordx4 v130, s[14:15]
	v_lshl_add_u64 v[212:213], s[14:15], 0, v[132:133]
	s_mov_b32 m0, s31
	global_load_lds_dwordx4 v132, s[14:15]
	s_mov_b32 m0, s33
	v_lshl_add_u64 v[216:217], s[16:17], 0, v[132:133]
	global_load_lds_dwordx4 v130, s[40:41]
	s_mov_b32 m0, s34
	s_nop 0
	global_load_lds_dwordx4 v132, s[40:41]
	v_lshl_add_u64 v[214:215], s[16:17], 0, v[130:131]
	s_mov_b32 m0, s5
	s_nop 0
	global_load_lds_dwordx4 v130, s[16:17]
	s_mov_b32 m0, s21
	s_nop 0
	global_load_lds_dwordx4 v132, s[16:17]
	s_waitcnt vmcnt(8)
	s_waitcnt lgkmcnt(0)
	s_barrier
	s_setprio 1
	s_waitcnt lgkmcnt(0)
	v_mfma_f32_16x16x32_bf16 v[62:65], v[146:149], v[178:181], v[62:65]
	v_mfma_f32_16x16x32_bf16 v[58:61], v[154:157], v[178:181], v[58:61]
	v_mfma_f32_16x16x32_bf16 v[54:57], v[146:149], v[186:189], v[54:57]
	v_mfma_f32_16x16x32_bf16 v[50:53], v[154:157], v[186:189], v[50:53]
	v_mfma_f32_16x16x32_bf16 v[34:37], v[146:149], v[194:197], v[34:37]
	v_mfma_f32_16x16x32_bf16 v[26:29], v[154:157], v[194:197], v[26:29]
	v_mfma_f32_16x16x32_bf16 v[22:25], v[146:149], v[202:205], v[22:25]
	v_mfma_f32_16x16x32_bf16 v[10:13], v[154:157], v[202:205], v[10:13]
	v_mfma_f32_16x16x32_bf16 v[62:65], v[150:153], v[182:185], v[62:65]
	v_mfma_f32_16x16x32_bf16 v[58:61], v[158:161], v[182:185], v[58:61]
	v_mfma_f32_16x16x32_bf16 v[54:57], v[150:153], v[190:193], v[54:57]
	v_mfma_f32_16x16x32_bf16 v[50:53], v[158:161], v[190:193], v[50:53]
	v_mfma_f32_16x16x32_bf16 v[34:37], v[150:153], v[198:201], v[34:37]
	v_mfma_f32_16x16x32_bf16 v[26:29], v[158:161], v[198:201], v[26:29]
	v_mfma_f32_16x16x32_bf16 v[22:25], v[150:153], v[206:209], v[22:25]
	v_mfma_f32_16x16x32_bf16 v[10:13], v[158:161], v[206:209], v[10:13]
	s_setprio 0
	s_add_u32 s16, s16, 0x40000
	s_addc_u32 s17, s17, 0
	s_setprio 1
	v_mfma_f32_16x16x32_bf16 v[46:49], v[162:165], v[178:181], v[46:49]
	v_mfma_f32_16x16x32_bf16 v[42:45], v[170:173], v[178:181], v[42:45]
	v_mfma_f32_16x16x32_bf16 v[38:41], v[162:165], v[186:189], v[38:41]
	v_mfma_f32_16x16x32_bf16 v[30:33], v[170:173], v[186:189], v[30:33]
	v_mfma_f32_16x16x32_bf16 v[18:21], v[162:165], v[194:197], v[18:21]
	v_mfma_f32_16x16x32_bf16 v[14:17], v[170:173], v[194:197], v[14:17]
	v_mfma_f32_16x16x32_bf16 v[6:9], v[162:165], v[202:205], v[6:9]
	v_mfma_f32_16x16x32_bf16 v[2:5], v[170:173], v[202:205], v[2:5]
	v_mfma_f32_16x16x32_bf16 v[46:49], v[166:169], v[182:185], v[46:49]
	v_mfma_f32_16x16x32_bf16 v[42:45], v[174:177], v[182:185], v[42:45]
	v_mfma_f32_16x16x32_bf16 v[38:41], v[166:169], v[190:193], v[38:41]
	v_mfma_f32_16x16x32_bf16 v[30:33], v[174:177], v[190:193], v[30:33]
	v_mfma_f32_16x16x32_bf16 v[18:21], v[166:169], v[198:201], v[18:21]
	v_mfma_f32_16x16x32_bf16 v[14:17], v[174:177], v[198:201], v[14:17]
	v_mfma_f32_16x16x32_bf16 v[6:9], v[166:169], v[206:209], v[6:9]
	v_mfma_f32_16x16x32_bf16 v[2:5], v[174:177], v[206:209], v[2:5]
	s_setprio 0
	s_barrier
	ds_read_b128 v[146:149], v143
	ds_read_b128 v[150:153], v143 offset:1024
	ds_read_b128 v[154:157], v143 offset:2048
	ds_read_b128 v[158:161], v143 offset:3072
	ds_read_b128 v[162:165], v144
	ds_read_b128 v[166:169], v144 offset:1024
	ds_read_b128 v[170:173], v144 offset:2048
	ds_read_b128 v[174:177], v144 offset:3072
	s_mov_b32 m0, s22
	ds_read_b128 v[178:181], v142 offset:32768
	ds_read_b128 v[182:185], v142 offset:33792
	ds_read_b128 v[186:189], v142 offset:34816
	ds_read_b128 v[190:193], v142 offset:35840
	ds_read_b128 v[194:197], v142 offset:36864
	ds_read_b128 v[198:201], v142 offset:37888
	ds_read_b128 v[202:205], v142 offset:38912
	ds_read_b128 v[206:209], v142 offset:39936
	global_load_lds_dwordx4 v130, s[16:17]
	s_mov_b32 m0, s23
	s_nop 0
	global_load_lds_dwordx4 v132, s[16:17]
	s_waitcnt vmcnt(8)
	s_waitcnt lgkmcnt(0)
	s_barrier
	s_setprio 1
	s_waitcnt lgkmcnt(0)
	v_mfma_f32_16x16x32_bf16 v[126:129], v[146:149], v[178:181], v[126:129]
	v_mfma_f32_16x16x32_bf16 v[122:125], v[154:157], v[178:181], v[122:125]
	v_mfma_f32_16x16x32_bf16 v[118:121], v[146:149], v[186:189], v[118:121]
	v_mfma_f32_16x16x32_bf16 v[114:117], v[154:157], v[186:189], v[114:117]
	v_mfma_f32_16x16x32_bf16 v[106:109], v[146:149], v[194:197], v[106:109]
	v_mfma_f32_16x16x32_bf16 v[98:101], v[154:157], v[194:197], v[98:101]
	v_mfma_f32_16x16x32_bf16 v[82:85], v[146:149], v[202:205], v[82:85]
	v_mfma_f32_16x16x32_bf16 v[74:77], v[154:157], v[202:205], v[74:77]
	v_mfma_f32_16x16x32_bf16 v[126:129], v[150:153], v[182:185], v[126:129]
	v_mfma_f32_16x16x32_bf16 v[122:125], v[158:161], v[182:185], v[122:125]
	v_mfma_f32_16x16x32_bf16 v[118:121], v[150:153], v[190:193], v[118:121]
	v_mfma_f32_16x16x32_bf16 v[114:117], v[158:161], v[190:193], v[114:117]
	v_mfma_f32_16x16x32_bf16 v[106:109], v[150:153], v[198:201], v[106:109]
	v_mfma_f32_16x16x32_bf16 v[98:101], v[158:161], v[198:201], v[98:101]
	v_mfma_f32_16x16x32_bf16 v[82:85], v[150:153], v[206:209], v[82:85]
	v_mfma_f32_16x16x32_bf16 v[74:77], v[158:161], v[206:209], v[74:77]
	s_setprio 0
	s_add_u32 s14, s14, 0x40080
	s_addc_u32 s15, s15, 0
	s_setprio 1
	v_mfma_f32_16x16x32_bf16 v[110:113], v[162:165], v[178:181], v[110:113]
	v_mfma_f32_16x16x32_bf16 v[102:105], v[170:173], v[178:181], v[102:105]
	v_mfma_f32_16x16x32_bf16 v[94:97], v[162:165], v[186:189], v[94:97]
	v_mfma_f32_16x16x32_bf16 v[90:93], v[170:173], v[186:189], v[90:93]
	v_mfma_f32_16x16x32_bf16 v[86:89], v[162:165], v[194:197], v[86:89]
	v_mfma_f32_16x16x32_bf16 v[78:81], v[170:173], v[194:197], v[78:81]
	v_mfma_f32_16x16x32_bf16 v[70:73], v[162:165], v[202:205], v[70:73]
	v_mfma_f32_16x16x32_bf16 v[66:69], v[170:173], v[202:205], v[66:69]
	v_mfma_f32_16x16x32_bf16 v[110:113], v[166:169], v[182:185], v[110:113]
	v_mfma_f32_16x16x32_bf16 v[102:105], v[174:177], v[182:185], v[102:105]
	v_mfma_f32_16x16x32_bf16 v[94:97], v[166:169], v[190:193], v[94:97]
	v_mfma_f32_16x16x32_bf16 v[90:93], v[174:177], v[190:193], v[90:93]
	v_mfma_f32_16x16x32_bf16 v[86:89], v[166:169], v[198:201], v[86:89]
	v_mfma_f32_16x16x32_bf16 v[78:81], v[174:177], v[198:201], v[78:81]
	v_mfma_f32_16x16x32_bf16 v[70:73], v[166:169], v[206:209], v[70:73]
	v_mfma_f32_16x16x32_bf16 v[66:69], v[174:177], v[206:209], v[66:69]
	s_setprio 0
	s_barrier
	s_mov_b32 m0, s35
	v_lshl_add_u64 v[210:211], v[210:211], 0, s[2:3]
	ds_read_b128 v[178:181], v142 offset:49152
	ds_read_b128 v[182:185], v142 offset:50176
	ds_read_b128 v[186:189], v142 offset:51200
	ds_read_b128 v[190:193], v142 offset:52224
	ds_read_b128 v[194:197], v142 offset:53248
	ds_read_b128 v[198:201], v142 offset:54272
	ds_read_b128 v[202:205], v142 offset:55296
	ds_read_b128 v[206:209], v142 offset:56320
	global_load_lds_dwordx4 v[210:211], off
	v_lshl_add_u64 v[210:211], v[212:213], 0, s[2:3]
	s_mov_b32 m0, s36
	global_load_lds_dwordx4 v[210:211], off
	s_mov_b32 m0, s37
	s_nop 0
	global_load_lds_dwordx4 v130, s[14:15]
	s_mov_b32 m0, s38
	s_nop 0
	global_load_lds_dwordx4 v132, s[14:15]
	v_lshl_add_u64 v[210:211], v[214:215], 0, s[2:3]
	s_mov_b32 m0, s24
	s_nop 0
	global_load_lds_dwordx4 v[210:211], off
	v_lshl_add_u64 v[210:211], v[216:217], 0, s[2:3]
	s_mov_b32 m0, s25
	s_nop 0
	global_load_lds_dwordx4 v[210:211], off
	s_waitcnt vmcnt(8)
	s_waitcnt lgkmcnt(0)
	s_barrier
	s_setprio 1
	s_waitcnt lgkmcnt(0)
	v_mfma_f32_16x16x32_bf16 v[62:65], v[146:149], v[178:181], v[62:65]
	v_mfma_f32_16x16x32_bf16 v[58:61], v[154:157], v[178:181], v[58:61]
	v_mfma_f32_16x16x32_bf16 v[54:57], v[146:149], v[186:189], v[54:57]
	v_mfma_f32_16x16x32_bf16 v[50:53], v[154:157], v[186:189], v[50:53]
	v_mfma_f32_16x16x32_bf16 v[34:37], v[146:149], v[194:197], v[34:37]
	v_mfma_f32_16x16x32_bf16 v[26:29], v[154:157], v[194:197], v[26:29]
	v_mfma_f32_16x16x32_bf16 v[22:25], v[146:149], v[202:205], v[22:25]
	v_mfma_f32_16x16x32_bf16 v[10:13], v[154:157], v[202:205], v[10:13]
	v_mfma_f32_16x16x32_bf16 v[62:65], v[150:153], v[182:185], v[62:65]
	v_mfma_f32_16x16x32_bf16 v[58:61], v[158:161], v[182:185], v[58:61]
	v_mfma_f32_16x16x32_bf16 v[54:57], v[150:153], v[190:193], v[54:57]
	v_mfma_f32_16x16x32_bf16 v[50:53], v[158:161], v[190:193], v[50:53]
	v_mfma_f32_16x16x32_bf16 v[34:37], v[150:153], v[198:201], v[34:37]
	v_mfma_f32_16x16x32_bf16 v[26:29], v[158:161], v[198:201], v[26:29]
	v_mfma_f32_16x16x32_bf16 v[22:25], v[150:153], v[206:209], v[22:25]
	v_mfma_f32_16x16x32_bf16 v[10:13], v[158:161], v[206:209], v[10:13]
	s_setprio 0
	s_add_i32 s27, s27, 2
	s_add_u32 s12, s12, 0x100
	s_addc_u32 s13, s13, 0
	s_setprio 1
	v_mfma_f32_16x16x32_bf16 v[46:49], v[162:165], v[178:181], v[46:49]
	v_mfma_f32_16x16x32_bf16 v[42:45], v[170:173], v[178:181], v[42:45]
	v_mfma_f32_16x16x32_bf16 v[38:41], v[162:165], v[186:189], v[38:41]
	v_mfma_f32_16x16x32_bf16 v[30:33], v[170:173], v[186:189], v[30:33]
	v_mfma_f32_16x16x32_bf16 v[18:21], v[162:165], v[194:197], v[18:21]
	v_mfma_f32_16x16x32_bf16 v[14:17], v[170:173], v[194:197], v[14:17]
	v_mfma_f32_16x16x32_bf16 v[6:9], v[162:165], v[202:205], v[6:9]
	v_mfma_f32_16x16x32_bf16 v[2:5], v[170:173], v[202:205], v[2:5]
	v_mfma_f32_16x16x32_bf16 v[46:49], v[166:169], v[182:185], v[46:49]
	v_mfma_f32_16x16x32_bf16 v[42:45], v[174:177], v[182:185], v[42:45]
	v_mfma_f32_16x16x32_bf16 v[38:41], v[166:169], v[190:193], v[38:41]
	v_mfma_f32_16x16x32_bf16 v[30:33], v[174:177], v[190:193], v[30:33]
	v_mfma_f32_16x16x32_bf16 v[18:21], v[166:169], v[198:201], v[18:21]
	v_mfma_f32_16x16x32_bf16 v[14:17], v[174:177], v[198:201], v[14:17]
	v_mfma_f32_16x16x32_bf16 v[6:9], v[166:169], v[206:209], v[6:9]
	v_mfma_f32_16x16x32_bf16 v[2:5], v[174:177], v[206:209], v[2:5]
	s_setprio 0
	s_barrier
	s_cmp_gt_u32 s27, 13
	s_cbranch_scc0 .LBB0_1250
	s_cmpk_lt_u32 s19, 0x100
	s_cbranch_scc0 .LBB0_1253
	s_barrier

.LBB0_1381:
	ds_read_b128 v[138:141], v147
	ds_read_b128 v[150:153], v147 offset:1024
	ds_read_b128 v[154:157], v147 offset:2048
	ds_read_b128 v[158:161], v147 offset:3072
	ds_read_b128 v[162:165], v148
	ds_read_b128 v[166:169], v148 offset:1024
	ds_read_b128 v[170:173], v148 offset:2048
	ds_read_b128 v[174:177], v148 offset:3072
	s_add_u32 s24, s2, 0xfffc0080
	s_addc_u32 s25, s3, -1
	s_cmp_eq_u32 s53, 12
	s_cselect_b32 s27, s17, s25
	s_cselect_b32 s26, s49, s24
	s_cselect_b32 s25, s15, s52
	s_cselect_b32 s24, s50, s51
	s_add_i32 m0, s23, 0xc000
	ds_read_b128 v[178:181], v149
	ds_read_b128 v[182:185], v149 offset:1024
	ds_read_b128 v[186:189], v149 offset:2048
	ds_read_b128 v[190:193], v149 offset:3072
	ds_read_b128 v[194:197], v149 offset:4096
	ds_read_b128 v[198:201], v149 offset:5120
	ds_read_b128 v[202:205], v149 offset:6144
	ds_read_b128 v[206:209], v149 offset:7168
	global_load_lds_dwordx4 v132, s[2:3]
	s_add_i32 m0, s23, 0xe000
	s_nop 0
	global_load_lds_dwordx4 v134, s[2:3]
	s_waitcnt vmcnt(8)
	s_waitcnt lgkmcnt(0)
	s_barrier
	s_setprio 1
	s_waitcnt lgkmcnt(0)
	v_mfma_f32_16x16x32_bf16 v[124:127], v[138:141], v[178:181], v[124:127]
	v_mfma_f32_16x16x32_bf16 v[120:123], v[154:157], v[178:181], v[120:123]
	v_mfma_f32_16x16x32_bf16 v[116:119], v[138:141], v[186:189], v[116:119]
	v_mfma_f32_16x16x32_bf16 v[112:115], v[154:157], v[186:189], v[112:115]
	v_mfma_f32_16x16x32_bf16 v[104:107], v[138:141], v[194:197], v[104:107]
	v_mfma_f32_16x16x32_bf16 v[96:99], v[154:157], v[194:197], v[96:99]
	v_mfma_f32_16x16x32_bf16 v[88:91], v[138:141], v[202:205], v[88:91]
	v_mfma_f32_16x16x32_bf16 v[80:83], v[154:157], v[202:205], v[80:83]
	v_mfma_f32_16x16x32_bf16 v[124:127], v[150:153], v[182:185], v[124:127]
	v_mfma_f32_16x16x32_bf16 v[120:123], v[158:161], v[182:185], v[120:123]
	v_mfma_f32_16x16x32_bf16 v[116:119], v[150:153], v[190:193], v[116:119]
	v_mfma_f32_16x16x32_bf16 v[112:115], v[158:161], v[190:193], v[112:115]
	v_mfma_f32_16x16x32_bf16 v[104:107], v[150:153], v[198:201], v[104:107]
	v_mfma_f32_16x16x32_bf16 v[96:99], v[158:161], v[198:201], v[96:99]
	v_mfma_f32_16x16x32_bf16 v[88:91], v[150:153], v[206:209], v[88:91]
	v_mfma_f32_16x16x32_bf16 v[80:83], v[158:161], v[206:209], v[80:83]
	s_setprio 0
	s_add_i32 s54, s4, s29
	s_add_i32 s56, s41, s29
	s_setprio 1
	v_mfma_f32_16x16x32_bf16 v[108:111], v[162:165], v[178:181], v[108:111]
	v_mfma_f32_16x16x32_bf16 v[100:103], v[170:173], v[178:181], v[100:103]
	v_mfma_f32_16x16x32_bf16 v[92:95], v[162:165], v[186:189], v[92:95]
	v_mfma_f32_16x16x32_bf16 v[84:87], v[170:173], v[186:189], v[84:87]
	v_mfma_f32_16x16x32_bf16 v[76:79], v[162:165], v[194:197], v[76:79]
	v_mfma_f32_16x16x32_bf16 v[72:75], v[170:173], v[194:197], v[72:75]
	v_mfma_f32_16x16x32_bf16 v[68:71], v[162:165], v[202:205], v[68:71]
	v_mfma_f32_16x16x32_bf16 v[64:67], v[170:173], v[202:205], v[64:67]
	v_mfma_f32_16x16x32_bf16 v[108:111], v[166:169], v[182:185], v[108:111]
	v_mfma_f32_16x16x32_bf16 v[100:103], v[174:177], v[182:185], v[100:103]
	v_mfma_f32_16x16x32_bf16 v[92:95], v[166:169], v[190:193], v[92:95]
	v_mfma_f32_16x16x32_bf16 v[84:87], v[174:177], v[190:193], v[84:87]
	v_mfma_f32_16x16x32_bf16 v[76:79], v[166:169], v[198:201], v[76:79]
	v_mfma_f32_16x16x32_bf16 v[72:75], v[174:177], v[198:201], v[72:75]
	v_mfma_f32_16x16x32_bf16 v[68:71], v[166:169], v[206:209], v[68:71]
	v_mfma_f32_16x16x32_bf16 v[64:67], v[174:177], v[206:209], v[64:67]
	s_setprio 0
	s_barrier
	s_mov_b32 m0, s54
	ds_read_b128 v[178:181], v149 offset:16384
	ds_read_b128 v[182:185], v149 offset:17408
	ds_read_b128 v[186:189], v149 offset:18432
	ds_read_b128 v[190:193], v149 offset:19456
	ds_read_b128 v[194:197], v149 offset:20480
	ds_read_b128 v[198:201], v149 offset:21504
	ds_read_b128 v[202:205], v149 offset:22528
	ds_read_b128 v[206:209], v149 offset:23552
	global_load_lds_dwordx4 v130, s[24:25]
	s_add_i32 m0, s54, 0x2000
	s_add_u32 s54, s24, 0x40000
	s_addc_u32 s55, s25, 0
	global_load_lds_dwordx4 v128, s[24:25]
	s_mov_b32 m0, s56
	v_lshl_add_u64 v[214:215], s[26:27], 0, v[128:129]
	global_load_lds_dwordx4 v130, s[54:55]
	s_add_i32 m0, s56, 0x2000
	s_nop 0
	global_load_lds_dwordx4 v128, s[54:55]
	v_lshl_add_u64 v[212:213], s[26:27], 0, v[130:131]
	s_mov_b32 m0, s23
	s_nop 0
	global_load_lds_dwordx4 v130, s[26:27]
	s_mov_b32 m0, s34
	s_nop 0
	global_load_lds_dwordx4 v128, s[26:27]
	s_waitcnt vmcnt(8)
	s_waitcnt lgkmcnt(0)
	s_barrier
	s_setprio 1
	s_waitcnt lgkmcnt(0)
	v_mfma_f32_16x16x32_bf16 v[60:63], v[138:141], v[178:181], v[60:63]
	v_mfma_f32_16x16x32_bf16 v[56:59], v[154:157], v[178:181], v[56:59]
	v_mfma_f32_16x16x32_bf16 v[52:55], v[138:141], v[186:189], v[52:55]
	v_mfma_f32_16x16x32_bf16 v[48:51], v[154:157], v[186:189], v[48:51]
	v_mfma_f32_16x16x32_bf16 v[44:47], v[138:141], v[194:197], v[44:47]
	v_mfma_f32_16x16x32_bf16 v[32:35], v[154:157], v[194:197], v[32:35]
	v_mfma_f32_16x16x32_bf16 v[20:23], v[138:141], v[202:205], v[20:23]
	v_mfma_f32_16x16x32_bf16 v[8:11], v[154:157], v[202:205], v[8:11]
	v_mfma_f32_16x16x32_bf16 v[60:63], v[150:153], v[182:185], v[60:63]
	v_mfma_f32_16x16x32_bf16 v[56:59], v[158:161], v[182:185], v[56:59]
	v_mfma_f32_16x16x32_bf16 v[52:55], v[150:153], v[190:193], v[52:55]
	v_mfma_f32_16x16x32_bf16 v[48:51], v[158:161], v[190:193], v[48:51]
	v_mfma_f32_16x16x32_bf16 v[44:47], v[150:153], v[198:201], v[44:47]
	v_mfma_f32_16x16x32_bf16 v[32:35], v[158:161], v[198:201], v[32:35]
	v_mfma_f32_16x16x32_bf16 v[20:23], v[150:153], v[206:209], v[20:23]
	v_mfma_f32_16x16x32_bf16 v[8:11], v[158:161], v[206:209], v[8:11]
	s_setprio 0
	s_add_i32 s54, 0, 0x18000
	s_add_i32 s55, 0, 0x1c000
	s_add_u32 s26, s26, 0x40000
	s_addc_u32 s27, s27, 0
	s_setprio 1
	v_mfma_f32_16x16x32_bf16 v[40:43], v[162:165], v[178:181], v[40:43]
	v_mfma_f32_16x16x32_bf16 v[36:39], v[170:173], v[178:181], v[36:39]
	v_mfma_f32_16x16x32_bf16 v[28:31], v[162:165], v[186:189], v[28:31]
	v_mfma_f32_16x16x32_bf16 v[24:27], v[170:173], v[186:189], v[24:27]
	v_mfma_f32_16x16x32_bf16 v[16:19], v[162:165], v[194:197], v[16:19]
	v_mfma_f32_16x16x32_bf16 v[12:15], v[170:173], v[194:197], v[12:15]
	v_mfma_f32_16x16x32_bf16 v[4:7], v[162:165], v[202:205], v[4:7]
	v_mfma_f32_16x16x32_bf16 v[0:3], v[170:173], v[202:205], v[0:3]
	v_mfma_f32_16x16x32_bf16 v[40:43], v[166:169], v[182:185], v[40:43]
	v_mfma_f32_16x16x32_bf16 v[36:39], v[174:177], v[182:185], v[36:39]
	v_mfma_f32_16x16x32_bf16 v[28:31], v[166:169], v[190:193], v[28:31]
	v_mfma_f32_16x16x32_bf16 v[24:27], v[174:177], v[190:193], v[24:27]
	v_mfma_f32_16x16x32_bf16 v[16:19], v[166:169], v[198:201], v[16:19]
	v_mfma_f32_16x16x32_bf16 v[12:15], v[174:177], v[198:201], v[12:15]
	v_mfma_f32_16x16x32_bf16 v[4:7], v[166:169], v[206:209], v[4:7]
	v_mfma_f32_16x16x32_bf16 v[0:3], v[174:177], v[206:209], v[0:3]
	s_setprio 0
	s_barrier
	v_add_u32_e32 v158, s54, v145
	v_add_u32_e32 v174, s55, v145
	ds_read_b128 v[138:141], v158
	ds_read_b128 v[150:153], v158 offset:1024
	ds_read_b128 v[154:157], v158 offset:2048
	ds_read_b128 v[158:161], v158 offset:3072
	ds_read_b128 v[162:165], v174
	ds_read_b128 v[166:169], v174 offset:1024
	ds_read_b128 v[170:173], v174 offset:2048
	ds_read_b128 v[174:177], v174 offset:3072
	s_mov_b32 m0, s35
	ds_read_b128 v[178:181], v149 offset:32768
	ds_read_b128 v[182:185], v149 offset:33792
	ds_read_b128 v[186:189], v149 offset:34816
	ds_read_b128 v[190:193], v149 offset:35840
	ds_read_b128 v[194:197], v149 offset:36864
	ds_read_b128 v[198:201], v149 offset:37888
	ds_read_b128 v[202:205], v149 offset:38912
	ds_read_b128 v[206:209], v149 offset:39936
	global_load_lds_dwordx4 v130, s[26:27]
	s_mov_b32 m0, s36
	s_nop 0
	global_load_lds_dwordx4 v128, s[26:27]
	s_waitcnt vmcnt(8)
	s_waitcnt lgkmcnt(0)
	s_barrier
	s_setprio 1
	s_waitcnt lgkmcnt(0)
	v_mfma_f32_16x16x32_bf16 v[124:127], v[138:141], v[178:181], v[124:127]
	v_mfma_f32_16x16x32_bf16 v[120:123], v[154:157], v[178:181], v[120:123]
	v_mfma_f32_16x16x32_bf16 v[116:119], v[138:141], v[186:189], v[116:119]
	v_mfma_f32_16x16x32_bf16 v[112:115], v[154:157], v[186:189], v[112:115]
	v_mfma_f32_16x16x32_bf16 v[104:107], v[138:141], v[194:197], v[104:107]
	v_mfma_f32_16x16x32_bf16 v[96:99], v[154:157], v[194:197], v[96:99]
	v_mfma_f32_16x16x32_bf16 v[88:91], v[138:141], v[202:205], v[88:91]
	v_mfma_f32_16x16x32_bf16 v[80:83], v[154:157], v[202:205], v[80:83]
	v_mfma_f32_16x16x32_bf16 v[124:127], v[150:153], v[182:185], v[124:127]
	v_mfma_f32_16x16x32_bf16 v[120:123], v[158:161], v[182:185], v[120:123]
	v_mfma_f32_16x16x32_bf16 v[116:119], v[150:153], v[190:193], v[116:119]
	v_mfma_f32_16x16x32_bf16 v[112:115], v[158:161], v[190:193], v[112:115]
	v_mfma_f32_16x16x32_bf16 v[104:107], v[150:153], v[198:201], v[104:107]
	v_mfma_f32_16x16x32_bf16 v[96:99], v[158:161], v[198:201], v[96:99]
	v_mfma_f32_16x16x32_bf16 v[88:91], v[150:153], v[206:209], v[88:91]
	v_mfma_f32_16x16x32_bf16 v[80:83], v[158:161], v[206:209], v[80:83]
	s_setprio 0
	s_add_i32 s26, s54, s29
	s_setprio 1
	v_mfma_f32_16x16x32_bf16 v[108:111], v[162:165], v[178:181], v[108:111]
	v_mfma_f32_16x16x32_bf16 v[100:103], v[170:173], v[178:181], v[100:103]
	v_mfma_f32_16x16x32_bf16 v[92:95], v[162:165], v[186:189], v[92:95]
	v_mfma_f32_16x16x32_bf16 v[84:87], v[170:173], v[186:189], v[84:87]
	v_mfma_f32_16x16x32_bf16 v[76:79], v[162:165], v[194:197], v[76:79]
	v_mfma_f32_16x16x32_bf16 v[72:75], v[170:173], v[194:197], v[72:75]
	v_mfma_f32_16x16x32_bf16 v[68:71], v[162:165], v[202:205], v[68:71]
	v_mfma_f32_16x16x32_bf16 v[64:67], v[170:173], v[202:205], v[64:67]
	v_mfma_f32_16x16x32_bf16 v[108:111], v[166:169], v[182:185], v[108:111]
	v_mfma_f32_16x16x32_bf16 v[100:103], v[174:177], v[182:185], v[100:103]
	v_mfma_f32_16x16x32_bf16 v[92:95], v[166:169], v[190:193], v[92:95]
	v_mfma_f32_16x16x32_bf16 v[84:87], v[174:177], v[190:193], v[84:87]
	v_mfma_f32_16x16x32_bf16 v[76:79], v[166:169], v[198:201], v[76:79]
	v_mfma_f32_16x16x32_bf16 v[72:75], v[174:177], v[198:201], v[72:75]
	v_mfma_f32_16x16x32_bf16 v[68:71], v[166:169], v[206:209], v[68:71]
	v_mfma_f32_16x16x32_bf16 v[64:67], v[174:177], v[206:209], v[64:67]
	s_setprio 0
	s_barrier
	s_add_i32 m0, s26, 0xffffff80
	ds_read_b128 v[178:181], v149 offset:49152
	ds_read_b128 v[182:185], v149 offset:50176
	ds_read_b128 v[186:189], v149 offset:51200
	ds_read_b128 v[190:193], v149 offset:52224
	ds_read_b128 v[194:197], v149 offset:53248
	ds_read_b128 v[198:201], v149 offset:54272
	ds_read_b128 v[202:205], v149 offset:55296
	ds_read_b128 v[206:209], v149 offset:56320
	global_load_lds_dwordx4 v130, s[24:25] offset:128
	s_add_i32 m0, s26, 0x1f80
	s_add_i32 s26, s55, s29
	global_load_lds_dwordx4 v128, s[24:25] offset:128
	s_add_u32 s24, s24, 0x40080
	s_addc_u32 s25, s25, 0
	s_mov_b32 m0, s26
	s_nop 0
	global_load_lds_dwordx4 v130, s[24:25]
	s_add_i32 m0, s26, 0x2000
	s_nop 0
	global_load_lds_dwordx4 v128, s[24:25]
	v_lshl_add_u64 v[142:143], v[212:213], 0, s[8:9]
	s_mov_b32 m0, s38
	s_nop 0
	global_load_lds_dwordx4 v[142:143], off
	v_lshl_add_u64 v[142:143], v[214:215], 0, s[8:9]
	s_mov_b32 m0, s39
	s_nop 0
	global_load_lds_dwordx4 v[142:143], off
	s_waitcnt vmcnt(8)
	s_waitcnt lgkmcnt(0)
	s_barrier
	s_setprio 1
	s_waitcnt lgkmcnt(0)
	v_mfma_f32_16x16x32_bf16 v[60:63], v[138:141], v[178:181], v[60:63]
	v_mfma_f32_16x16x32_bf16 v[56:59], v[154:157], v[178:181], v[56:59]
	v_mfma_f32_16x16x32_bf16 v[52:55], v[138:141], v[186:189], v[52:55]
	v_mfma_f32_16x16x32_bf16 v[48:51], v[154:157], v[186:189], v[48:51]
	v_mfma_f32_16x16x32_bf16 v[44:47], v[138:141], v[194:197], v[44:47]
	v_mfma_f32_16x16x32_bf16 v[32:35], v[154:157], v[194:197], v[32:35]
	v_mfma_f32_16x16x32_bf16 v[20:23], v[138:141], v[202:205], v[20:23]
	v_mfma_f32_16x16x32_bf16 v[8:11], v[154:157], v[202:205], v[8:11]
	v_mfma_f32_16x16x32_bf16 v[60:63], v[150:153], v[182:185], v[60:63]
	v_mfma_f32_16x16x32_bf16 v[56:59], v[158:161], v[182:185], v[56:59]
	v_mfma_f32_16x16x32_bf16 v[52:55], v[150:153], v[190:193], v[52:55]
	v_mfma_f32_16x16x32_bf16 v[48:51], v[158:161], v[190:193], v[48:51]
	v_mfma_f32_16x16x32_bf16 v[44:47], v[150:153], v[198:201], v[44:47]
	v_mfma_f32_16x16x32_bf16 v[32:35], v[158:161], v[198:201], v[32:35]
	v_mfma_f32_16x16x32_bf16 v[20:23], v[150:153], v[206:209], v[20:23]
	v_mfma_f32_16x16x32_bf16 v[8:11], v[158:161], v[206:209], v[8:11]
	s_setprio 0
	s_add_i32 s53, s53, 2
	s_add_u32 s2, s2, 0x100
	s_addc_u32 s3, s3, 0
	s_add_u32 s51, s51, 0x100
	s_addc_u32 s52, s52, 0
	s_setprio 1
	v_mfma_f32_16x16x32_bf16 v[40:43], v[162:165], v[178:181], v[40:43]
	v_mfma_f32_16x16x32_bf16 v[36:39], v[170:173], v[178:181], v[36:39]
	v_mfma_f32_16x16x32_bf16 v[28:31], v[162:165], v[186:189], v[28:31]
	v_mfma_f32_16x16x32_bf16 v[24:27], v[170:173], v[186:189], v[24:27]
	v_mfma_f32_16x16x32_bf16 v[16:19], v[162:165], v[194:197], v[16:19]
	v_mfma_f32_16x16x32_bf16 v[12:15], v[170:173], v[194:197], v[12:15]
	v_mfma_f32_16x16x32_bf16 v[4:7], v[162:165], v[202:205], v[4:7]
	v_mfma_f32_16x16x32_bf16 v[0:3], v[170:173], v[202:205], v[0:3]
	v_mfma_f32_16x16x32_bf16 v[40:43], v[166:169], v[182:185], v[40:43]
	v_mfma_f32_16x16x32_bf16 v[36:39], v[174:177], v[182:185], v[36:39]
	v_mfma_f32_16x16x32_bf16 v[28:31], v[166:169], v[190:193], v[28:31]
	v_mfma_f32_16x16x32_bf16 v[24:27], v[174:177], v[190:193], v[24:27]
	v_mfma_f32_16x16x32_bf16 v[16:19], v[166:169], v[198:201], v[16:19]
	v_mfma_f32_16x16x32_bf16 v[12:15], v[174:177], v[198:201], v[12:15]
	v_mfma_f32_16x16x32_bf16 v[4:7], v[166:169], v[206:209], v[4:7]
	v_mfma_f32_16x16x32_bf16 v[0:3], v[174:177], v[206:209], v[0:3]
	s_setprio 0
	s_barrier
	s_cmp_gt_u32 s53, 13
	s_cbranch_scc0 .LBB0_1381
	s_and_b64 vcc, exec, s[10:11]
	s_cbranch_vccz .LBB0_1384
	s_barrier
